# P10 sumsq prefetch + P9 residual prefetch (counted vmcnt waits)
# speedup vs baseline: 1.0059x; 1.0059x over previous
.LBB0_1220:
	ds_read_b128 v[142:145], v149
	ds_read_b128 v[154:157], v149 offset:1024
	ds_read_b128 v[158:161], v149 offset:2048
	ds_read_b128 v[166:169], v149 offset:3072
	ds_read_b128 v[170:173], v150
	ds_read_b128 v[174:177], v150 offset:1024
	ds_read_b128 v[178:181], v150 offset:2048
	ds_read_b128 v[182:185], v150 offset:3072
	s_add_u32 s30, s28, 0xfffe0080
	s_addc_u32 s31, s29, -1
	s_cmp_eq_u32 s51, 4
	s_cselect_b32 s35, s1, s31
	s_cselect_b32 s34, s17, s30
	s_cselect_b32 s31, s19, s50
	s_cselect_b32 s30, s48, s49
	v_lshl_add_u64 v[162:163], s[28:29], 0, v[138:139]
	s_add_i32 m0, s27, 0xc000
	ds_read_b128 v[186:189], v151
	ds_read_b128 v[190:193], v151 offset:1024
	ds_read_b128 v[194:197], v151 offset:2048
	ds_read_b128 v[198:201], v151 offset:3072
	ds_read_b128 v[202:205], v151 offset:4096
	ds_read_b128 v[206:209], v151 offset:5120
	ds_read_b128 v[210:213], v151 offset:6144
	ds_read_b128 v[214:217], v151 offset:7168
	global_load_lds_dwordx4 v[162:163], off
	v_lshl_add_u64 v[162:163], s[28:29], 0, v[140:141]
	s_add_i32 m0, s27, 0xe000
	s_nop 0
	global_load_lds_dwordx4 v[162:163], off
	s_waitcnt vmcnt(8)
	s_waitcnt lgkmcnt(0)
	s_barrier
	s_setprio 1
	s_waitcnt lgkmcnt(0)
	v_mfma_f32_16x16x32_bf16 v[126:129], v[142:145], v[186:189], v[126:129]
	v_mfma_f32_16x16x32_bf16 v[122:125], v[158:161], v[186:189], v[122:125]
	v_mfma_f32_16x16x32_bf16 v[110:113], v[142:145], v[194:197], v[110:113]
	v_mfma_f32_16x16x32_bf16 v[106:109], v[158:161], v[194:197], v[106:109]
	v_mfma_f32_16x16x32_bf16 v[94:97], v[142:145], v[202:205], v[94:97]
	v_mfma_f32_16x16x32_bf16 v[90:93], v[158:161], v[202:205], v[90:93]
	v_mfma_f32_16x16x32_bf16 v[78:81], v[142:145], v[210:213], v[78:81]
	v_mfma_f32_16x16x32_bf16 v[74:77], v[158:161], v[210:213], v[74:77]
	v_mfma_f32_16x16x32_bf16 v[126:129], v[154:157], v[190:193], v[126:129]
	v_mfma_f32_16x16x32_bf16 v[122:125], v[166:169], v[190:193], v[122:125]
	v_mfma_f32_16x16x32_bf16 v[110:113], v[154:157], v[198:201], v[110:113]
	v_mfma_f32_16x16x32_bf16 v[106:109], v[166:169], v[198:201], v[106:109]
	v_mfma_f32_16x16x32_bf16 v[94:97], v[154:157], v[206:209], v[94:97]
	v_mfma_f32_16x16x32_bf16 v[90:93], v[166:169], v[206:209], v[90:93]
	v_mfma_f32_16x16x32_bf16 v[78:81], v[154:157], v[214:217], v[78:81]
	v_mfma_f32_16x16x32_bf16 v[74:77], v[166:169], v[214:217], v[74:77]
	s_setprio 0
	s_setprio 1
	v_mfma_f32_16x16x32_bf16 v[118:121], v[170:173], v[186:189], v[118:121]
	v_mfma_f32_16x16x32_bf16 v[114:117], v[178:181], v[186:189], v[114:117]
	v_mfma_f32_16x16x32_bf16 v[102:105], v[170:173], v[194:197], v[102:105]
	v_mfma_f32_16x16x32_bf16 v[98:101], v[178:181], v[194:197], v[98:101]
	v_mfma_f32_16x16x32_bf16 v[86:89], v[170:173], v[202:205], v[86:89]
	v_mfma_f32_16x16x32_bf16 v[82:85], v[178:181], v[202:205], v[82:85]
	v_mfma_f32_16x16x32_bf16 v[70:73], v[170:173], v[210:213], v[70:73]
	v_mfma_f32_16x16x32_bf16 v[66:69], v[178:181], v[210:213], v[66:69]
	v_mfma_f32_16x16x32_bf16 v[118:121], v[174:177], v[190:193], v[118:121]
	v_mfma_f32_16x16x32_bf16 v[114:117], v[182:185], v[190:193], v[114:117]
	v_mfma_f32_16x16x32_bf16 v[102:105], v[174:177], v[198:201], v[102:105]
	v_mfma_f32_16x16x32_bf16 v[98:101], v[182:185], v[198:201], v[98:101]
	v_mfma_f32_16x16x32_bf16 v[86:89], v[174:177], v[206:209], v[86:89]
	v_mfma_f32_16x16x32_bf16 v[82:85], v[182:185], v[206:209], v[82:85]
	v_mfma_f32_16x16x32_bf16 v[70:73], v[174:177], v[214:217], v[70:73]
	v_mfma_f32_16x16x32_bf16 v[66:69], v[182:185], v[214:217], v[66:69]
	s_setprio 0
	s_barrier
	s_add_i32 s52, s46, s2
	v_lshl_add_u64 v[162:163], s[30:31], 0, v[132:133]
	s_mov_b32 m0, s52
	ds_read_b128 v[186:189], v151 offset:16384
	ds_read_b128 v[190:193], v151 offset:17408
	ds_read_b128 v[194:197], v151 offset:18432
	ds_read_b128 v[198:201], v151 offset:19456
	ds_read_b128 v[202:205], v151 offset:20480
	ds_read_b128 v[206:209], v151 offset:21504
	ds_read_b128 v[210:213], v151 offset:22528
	ds_read_b128 v[214:217], v151 offset:23552
	global_load_lds_dwordx4 v[162:163], off
	s_add_i32 m0, s52, 0x2000
	s_add_u32 s52, s30, 0x20000
	v_lshl_add_u64 v[218:219], s[30:31], 0, v[136:137]
	s_addc_u32 s53, s31, 0
	s_add_i32 s54, s47, s2
	global_load_lds_dwordx4 v[218:219], off
	v_lshl_add_u64 v[220:221], s[52:53], 0, v[132:133]
	s_mov_b32 m0, s54
	v_lshl_add_u64 v[222:223], s[34:35], 0, v[134:135]
	global_load_lds_dwordx4 v[220:221], off
	v_lshl_add_u64 v[220:221], s[52:53], 0, v[136:137]
	s_add_i32 m0, s54, 0x2000
	s_nop 0
	global_load_lds_dwordx4 v[220:221], off
	v_lshl_add_u64 v[220:221], s[34:35], 0, v[130:131]
	s_mov_b32 m0, s27
	s_nop 0
	global_load_lds_dwordx4 v[220:221], off
	s_mov_b32 m0, s37
	s_nop 0
	global_load_lds_dwordx4 v[222:223], off
	s_waitcnt vmcnt(8)
	s_waitcnt lgkmcnt(0)
	s_barrier
	s_setprio 1
	s_waitcnt lgkmcnt(0)
	v_mfma_f32_16x16x32_bf16 v[62:65], v[142:145], v[186:189], v[62:65]
	v_mfma_f32_16x16x32_bf16 v[58:61], v[158:161], v[186:189], v[58:61]
	v_mfma_f32_16x16x32_bf16 v[46:49], v[142:145], v[194:197], v[46:49]
	v_mfma_f32_16x16x32_bf16 v[42:45], v[158:161], v[194:197], v[42:45]
	v_mfma_f32_16x16x32_bf16 v[30:33], v[142:145], v[202:205], v[30:33]
	v_mfma_f32_16x16x32_bf16 v[26:29], v[158:161], v[202:205], v[26:29]
	v_mfma_f32_16x16x32_bf16 v[14:17], v[142:145], v[210:213], v[14:17]
	v_mfma_f32_16x16x32_bf16 v[10:13], v[158:161], v[210:213], v[10:13]
	v_mfma_f32_16x16x32_bf16 v[62:65], v[154:157], v[190:193], v[62:65]
	v_mfma_f32_16x16x32_bf16 v[58:61], v[166:169], v[190:193], v[58:61]
	v_mfma_f32_16x16x32_bf16 v[46:49], v[154:157], v[198:201], v[46:49]
	v_mfma_f32_16x16x32_bf16 v[42:45], v[166:169], v[198:201], v[42:45]
	v_mfma_f32_16x16x32_bf16 v[30:33], v[154:157], v[206:209], v[30:33]
	v_mfma_f32_16x16x32_bf16 v[26:29], v[166:169], v[206:209], v[26:29]
	v_mfma_f32_16x16x32_bf16 v[14:17], v[154:157], v[214:217], v[14:17]
	v_mfma_f32_16x16x32_bf16 v[10:13], v[166:169], v[214:217], v[10:13]
	s_setprio 0
	s_setprio 1
	v_mfma_f32_16x16x32_bf16 v[54:57], v[170:173], v[186:189], v[54:57]
	v_mfma_f32_16x16x32_bf16 v[50:53], v[178:181], v[186:189], v[50:53]
	v_mfma_f32_16x16x32_bf16 v[38:41], v[170:173], v[194:197], v[38:41]
	v_mfma_f32_16x16x32_bf16 v[34:37], v[178:181], v[194:197], v[34:37]
	v_mfma_f32_16x16x32_bf16 v[22:25], v[170:173], v[202:205], v[22:25]
	v_mfma_f32_16x16x32_bf16 v[18:21], v[178:181], v[202:205], v[18:21]
	v_mfma_f32_16x16x32_bf16 v[6:9], v[170:173], v[210:213], v[6:9]
	v_mfma_f32_16x16x32_bf16 v[2:5], v[178:181], v[210:213], v[2:5]
	v_mfma_f32_16x16x32_bf16 v[54:57], v[174:177], v[190:193], v[54:57]
	v_mfma_f32_16x16x32_bf16 v[50:53], v[182:185], v[190:193], v[50:53]
	v_mfma_f32_16x16x32_bf16 v[38:41], v[174:177], v[198:201], v[38:41]
	v_mfma_f32_16x16x32_bf16 v[34:37], v[182:185], v[198:201], v[34:37]
	v_mfma_f32_16x16x32_bf16 v[22:25], v[174:177], v[206:209], v[22:25]
	v_mfma_f32_16x16x32_bf16 v[18:21], v[182:185], v[206:209], v[18:21]
	v_mfma_f32_16x16x32_bf16 v[6:9], v[174:177], v[214:217], v[6:9]
	v_mfma_f32_16x16x32_bf16 v[2:5], v[182:185], v[214:217], v[2:5]
	s_setprio 0
	s_barrier
	s_add_i32 s52, 0, 0x18000
	v_add_u32_e32 v153, s52, v148
	s_add_i32 s53, 0, 0x1c000
	ds_read_b128 v[142:145], v153
	ds_read_b128 v[154:157], v153 offset:1024
	ds_read_b128 v[158:161], v153 offset:2048
	ds_read_b128 v[166:169], v153 offset:3072
	v_add_u32_e32 v153, s53, v148
	ds_read_b128 v[170:173], v153
	ds_read_b128 v[174:177], v153 offset:1024
	ds_read_b128 v[178:181], v153 offset:2048
	ds_read_b128 v[182:185], v153 offset:3072
	s_add_u32 s34, s34, 0x20000
	s_addc_u32 s35, s35, 0
	s_mov_b32 m0, s38
	v_lshl_add_u64 v[224:225], s[34:35], 0, v[130:131]
	ds_read_b128 v[186:189], v151 offset:32768
	ds_read_b128 v[190:193], v151 offset:33792
	ds_read_b128 v[194:197], v151 offset:34816
	ds_read_b128 v[198:201], v151 offset:35840
	ds_read_b128 v[202:205], v151 offset:36864
	ds_read_b128 v[206:209], v151 offset:37888
	ds_read_b128 v[210:213], v151 offset:38912
	ds_read_b128 v[214:217], v151 offset:39936
	global_load_lds_dwordx4 v[224:225], off
	v_lshl_add_u64 v[224:225], s[34:35], 0, v[134:135]
	s_mov_b32 m0, s39
	s_nop 0
	global_load_lds_dwordx4 v[224:225], off
	s_waitcnt vmcnt(8)
	s_waitcnt lgkmcnt(0)
	s_barrier
	s_setprio 1
	s_waitcnt lgkmcnt(0)
	v_mfma_f32_16x16x32_bf16 v[126:129], v[142:145], v[186:189], v[126:129]
	v_mfma_f32_16x16x32_bf16 v[122:125], v[158:161], v[186:189], v[122:125]
	v_mfma_f32_16x16x32_bf16 v[110:113], v[142:145], v[194:197], v[110:113]
	v_mfma_f32_16x16x32_bf16 v[106:109], v[158:161], v[194:197], v[106:109]
	v_mfma_f32_16x16x32_bf16 v[94:97], v[142:145], v[202:205], v[94:97]
	v_mfma_f32_16x16x32_bf16 v[90:93], v[158:161], v[202:205], v[90:93]
	v_mfma_f32_16x16x32_bf16 v[78:81], v[142:145], v[210:213], v[78:81]
	v_mfma_f32_16x16x32_bf16 v[74:77], v[158:161], v[210:213], v[74:77]
	v_mfma_f32_16x16x32_bf16 v[126:129], v[154:157], v[190:193], v[126:129]
	v_mfma_f32_16x16x32_bf16 v[122:125], v[166:169], v[190:193], v[122:125]
	v_mfma_f32_16x16x32_bf16 v[110:113], v[154:157], v[198:201], v[110:113]
	v_mfma_f32_16x16x32_bf16 v[106:109], v[166:169], v[198:201], v[106:109]
	v_mfma_f32_16x16x32_bf16 v[94:97], v[154:157], v[206:209], v[94:97]
	v_mfma_f32_16x16x32_bf16 v[90:93], v[166:169], v[206:209], v[90:93]
	v_mfma_f32_16x16x32_bf16 v[78:81], v[154:157], v[214:217], v[78:81]
	v_mfma_f32_16x16x32_bf16 v[74:77], v[166:169], v[214:217], v[74:77]
	s_setprio 0
	s_setprio 1
	v_mfma_f32_16x16x32_bf16 v[118:121], v[170:173], v[186:189], v[118:121]
	v_mfma_f32_16x16x32_bf16 v[114:117], v[178:181], v[186:189], v[114:117]
	v_mfma_f32_16x16x32_bf16 v[102:105], v[170:173], v[194:197], v[102:105]
	v_mfma_f32_16x16x32_bf16 v[98:101], v[178:181], v[194:197], v[98:101]
	v_mfma_f32_16x16x32_bf16 v[86:89], v[170:173], v[202:205], v[86:89]
	v_mfma_f32_16x16x32_bf16 v[82:85], v[178:181], v[202:205], v[82:85]
	v_mfma_f32_16x16x32_bf16 v[70:73], v[170:173], v[210:213], v[70:73]
	v_mfma_f32_16x16x32_bf16 v[66:69], v[178:181], v[210:213], v[66:69]
	v_mfma_f32_16x16x32_bf16 v[118:121], v[174:177], v[190:193], v[118:121]
	v_mfma_f32_16x16x32_bf16 v[114:117], v[182:185], v[190:193], v[114:117]
	v_mfma_f32_16x16x32_bf16 v[102:105], v[174:177], v[198:201], v[102:105]
	v_mfma_f32_16x16x32_bf16 v[98:101], v[182:185], v[198:201], v[98:101]
	v_mfma_f32_16x16x32_bf16 v[86:89], v[174:177], v[206:209], v[86:89]
	v_mfma_f32_16x16x32_bf16 v[82:85], v[182:185], v[206:209], v[82:85]
	v_mfma_f32_16x16x32_bf16 v[70:73], v[174:177], v[214:217], v[70:73]
	v_mfma_f32_16x16x32_bf16 v[66:69], v[182:185], v[214:217], v[66:69]
	s_setprio 0
	s_barrier
	s_add_i32 s34, s52, s2
	v_lshl_add_u64 v[162:163], v[162:163], 0, s[10:11]
	s_mov_b32 m0, s34
	ds_read_b128 v[186:189], v151 offset:49152
	ds_read_b128 v[190:193], v151 offset:50176
	ds_read_b128 v[194:197], v151 offset:51200
	ds_read_b128 v[198:201], v151 offset:52224
	ds_read_b128 v[202:205], v151 offset:53248
	ds_read_b128 v[206:209], v151 offset:54272
	ds_read_b128 v[210:213], v151 offset:55296
	ds_read_b128 v[214:217], v151 offset:56320
	global_load_lds_dwordx4 v[162:163], off
	s_add_i32 m0, s34, 0x2000
	s_add_u32 s30, s30, 0x20080
	v_lshl_add_u64 v[162:163], v[218:219], 0, s[10:11]
	s_addc_u32 s31, s31, 0
	s_add_i32 s34, s53, s2
	global_load_lds_dwordx4 v[162:163], off
	v_lshl_add_u64 v[162:163], s[30:31], 0, v[132:133]
	s_mov_b32 m0, s34
	s_nop 0
	global_load_lds_dwordx4 v[162:163], off
	v_lshl_add_u64 v[162:163], s[30:31], 0, v[136:137]
	s_add_i32 m0, s34, 0x2000
	s_nop 0
	global_load_lds_dwordx4 v[162:163], off
	v_lshl_add_u64 v[162:163], v[220:221], 0, s[10:11]
	s_mov_b32 m0, s43
	s_nop 0
	global_load_lds_dwordx4 v[162:163], off
	v_lshl_add_u64 v[162:163], v[222:223], 0, s[10:11]
	s_mov_b32 m0, s44
	s_nop 0
	global_load_lds_dwordx4 v[162:163], off
	s_waitcnt vmcnt(8)
	s_waitcnt lgkmcnt(0)
	s_barrier
	s_setprio 1
	s_waitcnt lgkmcnt(0)
	v_mfma_f32_16x16x32_bf16 v[62:65], v[142:145], v[186:189], v[62:65]
	v_mfma_f32_16x16x32_bf16 v[58:61], v[158:161], v[186:189], v[58:61]
	v_mfma_f32_16x16x32_bf16 v[46:49], v[142:145], v[194:197], v[46:49]
	v_mfma_f32_16x16x32_bf16 v[42:45], v[158:161], v[194:197], v[42:45]
	v_mfma_f32_16x16x32_bf16 v[30:33], v[142:145], v[202:205], v[30:33]
	v_mfma_f32_16x16x32_bf16 v[26:29], v[158:161], v[202:205], v[26:29]
	v_mfma_f32_16x16x32_bf16 v[14:17], v[142:145], v[210:213], v[14:17]
	v_mfma_f32_16x16x32_bf16 v[10:13], v[158:161], v[210:213], v[10:13]
	v_mfma_f32_16x16x32_bf16 v[62:65], v[154:157], v[190:193], v[62:65]
	v_mfma_f32_16x16x32_bf16 v[58:61], v[166:169], v[190:193], v[58:61]
	v_mfma_f32_16x16x32_bf16 v[46:49], v[154:157], v[198:201], v[46:49]
	v_mfma_f32_16x16x32_bf16 v[42:45], v[166:169], v[198:201], v[42:45]
	v_mfma_f32_16x16x32_bf16 v[30:33], v[154:157], v[206:209], v[30:33]
	v_mfma_f32_16x16x32_bf16 v[26:29], v[166:169], v[206:209], v[26:29]
	v_mfma_f32_16x16x32_bf16 v[14:17], v[154:157], v[214:217], v[14:17]
	v_mfma_f32_16x16x32_bf16 v[10:13], v[166:169], v[214:217], v[10:13]
	s_setprio 0
	s_setprio 1
	v_mfma_f32_16x16x32_bf16 v[54:57], v[170:173], v[186:189], v[54:57]
	v_mfma_f32_16x16x32_bf16 v[50:53], v[178:181], v[186:189], v[50:53]
	v_mfma_f32_16x16x32_bf16 v[38:41], v[170:173], v[194:197], v[38:41]
	v_mfma_f32_16x16x32_bf16 v[34:37], v[178:181], v[194:197], v[34:37]
	v_mfma_f32_16x16x32_bf16 v[22:25], v[170:173], v[202:205], v[22:25]
	v_mfma_f32_16x16x32_bf16 v[18:21], v[178:181], v[202:205], v[18:21]
	v_mfma_f32_16x16x32_bf16 v[6:9], v[170:173], v[210:213], v[6:9]
	v_mfma_f32_16x16x32_bf16 v[2:5], v[178:181], v[210:213], v[2:5]
	v_mfma_f32_16x16x32_bf16 v[54:57], v[174:177], v[190:193], v[54:57]
	v_mfma_f32_16x16x32_bf16 v[50:53], v[182:185], v[190:193], v[50:53]
	v_mfma_f32_16x16x32_bf16 v[38:41], v[174:177], v[198:201], v[38:41]
	v_mfma_f32_16x16x32_bf16 v[34:37], v[182:185], v[198:201], v[34:37]
	v_mfma_f32_16x16x32_bf16 v[22:25], v[174:177], v[206:209], v[22:25]
	v_mfma_f32_16x16x32_bf16 v[18:21], v[182:185], v[206:209], v[18:21]
	v_mfma_f32_16x16x32_bf16 v[6:9], v[174:177], v[214:217], v[6:9]
	v_mfma_f32_16x16x32_bf16 v[2:5], v[182:185], v[214:217], v[2:5]
	s_setprio 0
	s_barrier
	s_add_i32 s51, s51, 2
	s_add_u32 s28, s28, 0x100
	s_addc_u32 s29, s29, 0
	s_add_u32 s49, s49, 0x100
	s_addc_u32 s50, s50, 0
	s_cmp_gt_u32 s51, 5
	s_cbranch_scc0 .LBB0_1220
	s_lshl_b32 s98, s26, 8
	s_add_i32 s98, s98, s41
	v_add_u32_e32 v240, s98, v146
	s_lshl_b32 s98, s0, 8
	s_or_b32 s98, s98, s42
	v_lshl_add_u32 v241, v147, 3, s98
	v_lshlrev_b32_e32 v240, 12, v240
	v_lshl_add_u32 v240, v241, 1, v240
	global_load_dwordx4 v[168:171], v240, s[62:63]
	global_load_dwordx4 v[172:175], v240, s[62:63] offset:256
	v_add_u32_e32 v240, 0x10000, v240
	global_load_dwordx4 v[176:179], v240, s[62:63]
	global_load_dwordx4 v[180:183], v240, s[62:63] offset:256
	v_add_u32_e32 v240, 0x10000, v240
	global_load_dwordx4 v[184:187], v240, s[62:63]
	global_load_dwordx4 v[188:191], v240, s[62:63] offset:256
	v_add_u32_e32 v240, 0x10000, v240
	global_load_dwordx4 v[192:195], v240, s[62:63]
	global_load_dwordx4 v[196:199], v240, s[62:63] offset:256
	v_add_u32_e32 v240, 0x50000, v240
	global_load_dwordx4 v[200:203], v240, s[62:63]
	global_load_dwordx4 v[204:207], v240, s[62:63] offset:256
	v_add_u32_e32 v240, 0x10000, v240
	global_load_dwordx4 v[208:211], v240, s[62:63]
	global_load_dwordx4 v[212:215], v240, s[62:63] offset:256
	v_add_u32_e32 v240, 0x10000, v240
	global_load_dwordx4 v[216:219], v240, s[62:63]
	global_load_dwordx4 v[220:223], v240, s[62:63] offset:256
	v_add_u32_e32 v240, 0x10000, v240
	global_load_dwordx4 v[224:227], v240, s[62:63]
	global_load_dwordx4 v[232:235], v240, s[62:63] offset:256
	s_and_b64 vcc, exec, s[12:13]
	s_cbranch_vccz .LBB0_1223
	s_barrier
.LBB0_1223:
	v_mov_b32_e32 v142, v1
	v_mov_b32_e32 v153, v147
	v_mov_b32_e32 v143, v165
	v_mov_b32_e32 v144, v146
	s_lshl_b32 s1, s26, 8
	s_add_i32 s1, s1, s41
	v_add_u32_e32 v144, s1, v144
	s_lshl_b32 s0, s0, 8
	s_or_b32 s0, s0, s42
	v_ashrrev_i32_e32 v145, 31, v144
	v_lshl_add_u32 v142, v153, 3, s0
	v_lshlrev_b64 v[154:155], 12, v[144:145]
	v_lshl_add_u64 v[154:155], s[62:63], 0, v[154:155]
	v_ashrrev_i32_e32 v143, 31, v142
	v_lshl_add_u64 v[158:159], v[142:143], 1, v[154:155]
	s_nop 0
	v_cmp_eq_u32_e32 vcc, 0, v153
	v_xor_b32_e32 v164, 32, v152
	s_waitcnt vmcnt(15)
	v_lshlrev_b32_e32 v160, 16, v168
	v_and_b32_e32 v161, 0xffff0000, v168
	v_lshlrev_b32_e32 v154, 16, v169
	v_and_b32_e32 v155, 0xffff0000, v169
	v_lshlrev_b32_e32 v162, 16, v170
	v_and_b32_e32 v163, 0xffff0000, v170
	v_lshlrev_b32_e32 v156, 16, v171
	v_and_b32_e32 v157, 0xffff0000, v171
	v_pk_add_f32 v[128:129], v[128:129], v[154:155]
	v_pk_add_f32 v[160:161], v[126:127], v[160:161]
	v_pk_add_f32 v[166:167], v[124:125], v[156:157]
	v_pk_add_f32 v[162:163], v[122:123], v[162:163]
	v_cvt_pk_bf16_f32 v124, v160, v161
	v_cvt_pk_bf16_f32 v125, v128, v129
	v_mul_f32_e32 v153, v161, v161
	v_cvt_pk_bf16_f32 v126, v162, v163
	v_cvt_pk_bf16_f32 v127, v166, v167
	s_nop 0
	v_mul_f32_e32 v129, v129, v129
	v_mul_f32_e32 v161, v163, v163
	v_fmac_f32_e32 v153, v160, v160
	v_fmac_f32_e32 v129, v128, v128
	v_mul_f32_e32 v163, v167, v167
	v_fmac_f32_e32 v161, v162, v162
	v_add_f32_e32 v128, v153, v129
	v_fmac_f32_e32 v163, v166, v166
	v_add_f32_e32 v128, v161, v128
	v_add_f32_e32 v153, v163, v128
	v_and_b32_e32 v123, 64, v152
	v_xor_b32_e32 v122, 16, v152
	v_add_u32_e32 v123, 64, v123
	v_cmp_lt_i32_e64 s[0:1], v122, v123
	global_store_dwordx4 v[158:159], v[124:127], off
	s_waitcnt vmcnt(15)
	v_lshlrev_b32_e32 v128, 16, v172
	v_and_b32_e32 v129, 0xffff0000, v172
	v_lshlrev_b32_e32 v154, 16, v173
	v_and_b32_e32 v155, 0xffff0000, v173
	v_lshlrev_b32_e32 v160, 16, v174
	v_and_b32_e32 v161, 0xffff0000, v174
	v_pk_add_f32 v[120:121], v[120:121], v[154:155]
	v_pk_add_f32 v[118:119], v[118:119], v[128:129]
	v_lshlrev_b32_e32 v156, 16, v175
	v_and_b32_e32 v157, 0xffff0000, v175
	v_pk_add_f32 v[154:155], v[114:115], v[160:161]
	v_mul_f32_e32 v114, v119, v119
	v_mul_f32_e32 v115, v121, v121
	v_pk_add_f32 v[128:129], v[116:117], v[156:157]
	v_mul_f32_e32 v116, v155, v155
	v_fmac_f32_e32 v114, v118, v118
	v_fmac_f32_e32 v115, v120, v120
	v_mul_f32_e32 v117, v129, v129
	v_fmac_f32_e32 v116, v154, v154
	v_add_f32_e32 v114, v114, v115
	v_fmac_f32_e32 v117, v128, v128
	v_add_f32_e32 v114, v116, v114
	v_cndmask_b32_e64 v122, v152, v122, s[0:1]
	v_add_f32_e32 v114, v117, v114
	v_lshlrev_b32_e32 v122, 2, v122
	v_add_f32_e32 v114, v153, v114
	ds_bpermute_b32 v115, v122, v114
	v_cmp_lt_i32_e64 s[0:1], v164, v123
	v_cvt_pk_bf16_f32 v118, v118, v119
	v_cvt_pk_bf16_f32 v119, v120, v121
	v_cvt_pk_bf16_f32 v120, v154, v155
	s_waitcnt lgkmcnt(0)
	v_add_f32_e32 v114, v114, v115
	v_cvt_pk_bf16_f32 v121, v128, v129
	v_cndmask_b32_e64 v116, v152, v164, s[0:1]
	v_lshlrev_b32_e32 v116, 2, v116
	ds_bpermute_b32 v115, v116, v114
	global_store_dwordx4 v[158:159], v[118:121], off offset:256
	s_and_saveexec_b64 s[0:1], vcc
	s_cbranch_execz .LBB0_1225
	v_lshl_add_u64 v[118:119], v[144:145], 2, s[8:9]
	s_waitcnt lgkmcnt(0)
	v_add_f32_e32 v114, v114, v115
	global_atomic_add_f32 v[118:119], v114, off
.LBB0_1225:
	s_or_b64 exec, exec, s[0:1]
	v_add_u32_e32 v114, 16, v144
	s_waitcnt lgkmcnt(0)
	v_ashrrev_i32_e32 v115, 31, v114
	v_lshlrev_b64 v[118:119], 12, v[114:115]
	v_lshl_add_u64 v[118:119], s[62:63], 0, v[118:119]
	v_lshl_add_u64 v[124:125], v[142:143], 1, v[118:119]
	s_nop 0
	s_waitcnt vmcnt(16)
	v_lshlrev_b32_e32 v126, 16, v176
	v_and_b32_e32 v127, 0xffff0000, v176
	v_lshlrev_b32_e32 v118, 16, v177
	v_and_b32_e32 v119, 0xffff0000, v177
	v_lshlrev_b32_e32 v128, 16, v178
	v_and_b32_e32 v129, 0xffff0000, v178
	v_lshlrev_b32_e32 v120, 16, v179
	v_and_b32_e32 v121, 0xffff0000, v179
	v_pk_add_f32 v[118:119], v[112:113], v[118:119]
	v_pk_add_f32 v[126:127], v[110:111], v[126:127]
	v_pk_add_f32 v[120:121], v[108:109], v[120:121]
	v_pk_add_f32 v[128:129], v[106:107], v[128:129]
	v_cvt_pk_bf16_f32 v106, v126, v127
	v_cvt_pk_bf16_f32 v107, v118, v119
	v_mul_f32_e32 v117, v127, v127
	v_cvt_pk_bf16_f32 v108, v128, v129
	v_cvt_pk_bf16_f32 v109, v120, v121
	s_nop 0
	v_mul_f32_e32 v119, v119, v119
	v_mul_f32_e32 v123, v129, v129
	v_fmac_f32_e32 v117, v126, v126
	v_fmac_f32_e32 v119, v118, v118
	v_mul_f32_e32 v121, v121, v121
	v_fmac_f32_e32 v123, v128, v128
	v_add_f32_e32 v117, v117, v119
	v_fmac_f32_e32 v121, v120, v120
	v_add_f32_e32 v117, v123, v117
	v_add_f32_e32 v117, v121, v117
	global_store_dwordx4 v[124:125], v[106:109], off
	s_waitcnt vmcnt(16)
	v_lshlrev_b32_e32 v118, 16, v180
	v_and_b32_e32 v119, 0xffff0000, v180
	v_lshlrev_b32_e32 v110, 16, v181
	v_and_b32_e32 v111, 0xffff0000, v181
	v_lshlrev_b32_e32 v120, 16, v182
	v_and_b32_e32 v121, 0xffff0000, v182
	v_lshlrev_b32_e32 v112, 16, v183
	v_and_b32_e32 v113, 0xffff0000, v183
	v_pk_add_f32 v[104:105], v[104:105], v[110:111]
	v_pk_add_f32 v[102:103], v[102:103], v[118:119]
	v_pk_add_f32 v[110:111], v[100:101], v[112:113]
	v_pk_add_f32 v[112:113], v[98:99], v[120:121]
	v_mul_f32_e32 v98, v103, v103
	v_mul_f32_e32 v99, v105, v105
	v_mul_f32_e32 v100, v113, v113
	v_fmac_f32_e32 v98, v102, v102
	v_fmac_f32_e32 v99, v104, v104
	v_mul_f32_e32 v101, v111, v111
	v_fmac_f32_e32 v100, v112, v112
	v_add_f32_e32 v98, v98, v99
	v_add_f32_e32 v98, v100, v98
	v_fmac_f32_e32 v101, v110, v110
	v_add_f32_e32 v98, v101, v98
	v_add_f32_e32 v98, v117, v98
	ds_bpermute_b32 v99, v122, v98
	v_cvt_pk_bf16_f32 v100, v102, v103
	v_cvt_pk_bf16_f32 v101, v104, v105
	v_cvt_pk_bf16_f32 v102, v112, v113
	v_cvt_pk_bf16_f32 v103, v110, v111
	s_waitcnt lgkmcnt(0)
	v_add_f32_e32 v98, v98, v99
	ds_bpermute_b32 v99, v116, v98
	global_store_dwordx4 v[124:125], v[100:103], off offset:256
	s_and_saveexec_b64 s[0:1], vcc
	s_cbranch_execz .LBB0_1227
	v_lshl_add_u64 v[100:101], v[114:115], 2, s[8:9]
	s_waitcnt lgkmcnt(0)
	v_add_f32_e32 v98, v98, v99
	global_atomic_add_f32 v[100:101], v98, off
.LBB0_1227:
	s_or_b64 exec, exec, s[0:1]
	v_add_u32_e32 v98, 32, v144
	s_waitcnt lgkmcnt(0)
	v_ashrrev_i32_e32 v99, 31, v98
	v_lshlrev_b64 v[100:101], 12, v[98:99]
	v_lshl_add_u64 v[100:101], s[62:63], 0, v[100:101]
	v_lshl_add_u64 v[104:105], v[142:143], 1, v[100:101]
	s_nop 0
	s_waitcnt vmcnt(17)
	v_lshlrev_b32_e32 v106, 16, v184
	v_and_b32_e32 v107, 0xffff0000, v184
	v_lshlrev_b32_e32 v100, 16, v185
	v_and_b32_e32 v101, 0xffff0000, v185
	v_lshlrev_b32_e32 v108, 16, v186
	v_and_b32_e32 v109, 0xffff0000, v186
	v_lshlrev_b32_e32 v102, 16, v187
	v_and_b32_e32 v103, 0xffff0000, v187
	v_pk_add_f32 v[100:101], v[96:97], v[100:101]
	v_pk_add_f32 v[106:107], v[94:95], v[106:107]
	v_pk_add_f32 v[102:103], v[92:93], v[102:103]
	v_pk_add_f32 v[108:109], v[90:91], v[108:109]
	v_cvt_pk_bf16_f32 v90, v106, v107
	v_cvt_pk_bf16_f32 v91, v100, v101
	v_mul_f32_e32 v107, v107, v107
	v_cvt_pk_bf16_f32 v92, v108, v109
	v_cvt_pk_bf16_f32 v93, v102, v103
	s_nop 0
	v_mul_f32_e32 v101, v101, v101
	v_mul_f32_e32 v109, v109, v109
	v_fmac_f32_e32 v107, v106, v106
	v_fmac_f32_e32 v101, v100, v100
	v_mul_f32_e32 v103, v103, v103
	v_fmac_f32_e32 v109, v108, v108
	v_add_f32_e32 v100, v107, v101
	v_fmac_f32_e32 v103, v102, v102
	v_add_f32_e32 v100, v109, v100
	v_add_f32_e32 v106, v103, v100
	global_store_dwordx4 v[104:105], v[90:93], off
	s_waitcnt vmcnt(17)
	v_lshlrev_b32_e32 v100, 16, v188
	v_and_b32_e32 v101, 0xffff0000, v188
	v_lshlrev_b32_e32 v94, 16, v189
	v_and_b32_e32 v95, 0xffff0000, v189
	v_lshlrev_b32_e32 v102, 16, v190
	v_and_b32_e32 v103, 0xffff0000, v190
	v_lshlrev_b32_e32 v96, 16, v191
	v_and_b32_e32 v97, 0xffff0000, v191
	v_pk_add_f32 v[88:89], v[88:89], v[94:95]
	v_pk_add_f32 v[86:87], v[86:87], v[100:101]
	v_pk_add_f32 v[94:95], v[84:85], v[96:97]
	v_pk_add_f32 v[96:97], v[82:83], v[102:103]
	v_mul_f32_e32 v82, v87, v87
	v_mul_f32_e32 v83, v89, v89
	v_mul_f32_e32 v84, v97, v97
	v_fmac_f32_e32 v82, v86, v86
	v_fmac_f32_e32 v83, v88, v88
	v_mul_f32_e32 v85, v95, v95
	v_fmac_f32_e32 v84, v96, v96
	v_add_f32_e32 v82, v82, v83
	v_add_f32_e32 v82, v84, v82
	v_fmac_f32_e32 v85, v94, v94
	v_add_f32_e32 v82, v85, v82
	v_add_f32_e32 v82, v106, v82
	ds_bpermute_b32 v83, v122, v82
	v_cvt_pk_bf16_f32 v84, v86, v87
	v_cvt_pk_bf16_f32 v85, v88, v89
	v_cvt_pk_bf16_f32 v86, v96, v97
	v_cvt_pk_bf16_f32 v87, v94, v95
	s_waitcnt lgkmcnt(0)
	v_add_f32_e32 v82, v82, v83
	ds_bpermute_b32 v83, v116, v82
	global_store_dwordx4 v[104:105], v[84:87], off offset:256
	s_and_saveexec_b64 s[0:1], vcc
	s_cbranch_execz .LBB0_1229
	v_lshl_add_u64 v[84:85], v[98:99], 2, s[8:9]
	s_waitcnt lgkmcnt(0)
	v_add_f32_e32 v82, v82, v83
	global_atomic_add_f32 v[84:85], v82, off
.LBB0_1229:
	s_or_b64 exec, exec, s[0:1]
	v_add_u32_e32 v82, 48, v144
	s_waitcnt lgkmcnt(0)
	v_ashrrev_i32_e32 v83, 31, v82
	v_lshlrev_b64 v[84:85], 12, v[82:83]
	v_lshl_add_u64 v[84:85], s[62:63], 0, v[84:85]
	v_lshl_add_u64 v[88:89], v[142:143], 1, v[84:85]
	s_nop 0
	s_waitcnt vmcnt(18)
	v_lshlrev_b32_e32 v90, 16, v192
	v_and_b32_e32 v91, 0xffff0000, v192
	v_lshlrev_b32_e32 v84, 16, v193
	v_and_b32_e32 v85, 0xffff0000, v193
	v_lshlrev_b32_e32 v92, 16, v194
	v_and_b32_e32 v93, 0xffff0000, v194
	v_lshlrev_b32_e32 v86, 16, v195
	v_and_b32_e32 v87, 0xffff0000, v195
	v_pk_add_f32 v[84:85], v[80:81], v[84:85]
	v_pk_add_f32 v[90:91], v[78:79], v[90:91]
	v_pk_add_f32 v[86:87], v[76:77], v[86:87]
	v_pk_add_f32 v[92:93], v[74:75], v[92:93]
	v_cvt_pk_bf16_f32 v74, v90, v91
	v_cvt_pk_bf16_f32 v75, v84, v85
	v_mul_f32_e32 v91, v91, v91
	v_cvt_pk_bf16_f32 v76, v92, v93
	v_cvt_pk_bf16_f32 v77, v86, v87
	s_nop 0
	v_mul_f32_e32 v85, v85, v85
	v_mul_f32_e32 v93, v93, v93
	v_fmac_f32_e32 v91, v90, v90
	v_fmac_f32_e32 v85, v84, v84
	v_mul_f32_e32 v87, v87, v87
	v_fmac_f32_e32 v93, v92, v92
	v_add_f32_e32 v84, v91, v85
	v_fmac_f32_e32 v87, v86, v86
	v_add_f32_e32 v84, v93, v84
	v_add_f32_e32 v90, v87, v84
	global_store_dwordx4 v[88:89], v[74:77], off
	s_waitcnt vmcnt(18)
	v_lshlrev_b32_e32 v84, 16, v196
	v_and_b32_e32 v85, 0xffff0000, v196
	v_lshlrev_b32_e32 v78, 16, v197
	v_and_b32_e32 v79, 0xffff0000, v197
	v_lshlrev_b32_e32 v86, 16, v198
	v_and_b32_e32 v87, 0xffff0000, v198
	v_lshlrev_b32_e32 v80, 16, v199
	v_and_b32_e32 v81, 0xffff0000, v199
	v_pk_add_f32 v[72:73], v[72:73], v[78:79]
	v_pk_add_f32 v[70:71], v[70:71], v[84:85]
	v_pk_add_f32 v[78:79], v[68:69], v[80:81]
	v_pk_add_f32 v[80:81], v[66:67], v[86:87]
	v_mul_f32_e32 v66, v71, v71
	v_mul_f32_e32 v67, v73, v73
	v_mul_f32_e32 v68, v81, v81
	v_fmac_f32_e32 v66, v70, v70
	v_fmac_f32_e32 v67, v72, v72
	v_mul_f32_e32 v69, v79, v79
	v_fmac_f32_e32 v68, v80, v80
	v_add_f32_e32 v66, v66, v67
	v_add_f32_e32 v66, v68, v66
	v_fmac_f32_e32 v69, v78, v78
	v_add_f32_e32 v66, v69, v66
	v_add_f32_e32 v66, v90, v66
	ds_bpermute_b32 v67, v122, v66
	v_cvt_pk_bf16_f32 v68, v70, v71
	v_cvt_pk_bf16_f32 v69, v72, v73
	v_cvt_pk_bf16_f32 v70, v80, v81
	v_cvt_pk_bf16_f32 v71, v78, v79
	s_waitcnt lgkmcnt(0)
	v_add_f32_e32 v66, v66, v67
	ds_bpermute_b32 v67, v116, v66
	global_store_dwordx4 v[88:89], v[68:71], off offset:256
	s_and_saveexec_b64 s[0:1], vcc
	s_cbranch_execz .LBB0_1231
	v_lshl_add_u64 v[68:69], v[82:83], 2, s[8:9]
	s_waitcnt lgkmcnt(0)
	v_add_f32_e32 v66, v66, v67
	global_atomic_add_f32 v[68:69], v66, off
.LBB0_1231:
	s_or_b64 exec, exec, s[0:1]
	v_add_u32_e32 v66, 0x80, v144
	s_waitcnt lgkmcnt(0)
	v_ashrrev_i32_e32 v67, 31, v66
	v_lshlrev_b64 v[68:69], 12, v[66:67]
	v_lshl_add_u64 v[68:69], s[62:63], 0, v[68:69]
	v_lshl_add_u64 v[72:73], v[142:143], 1, v[68:69]
	s_nop 0
	s_waitcnt vmcnt(19)
	v_lshlrev_b32_e32 v74, 16, v200
	v_and_b32_e32 v75, 0xffff0000, v200
	v_lshlrev_b32_e32 v68, 16, v201
	v_and_b32_e32 v69, 0xffff0000, v201
	v_lshlrev_b32_e32 v76, 16, v202
	v_and_b32_e32 v77, 0xffff0000, v202
	v_lshlrev_b32_e32 v70, 16, v203
	v_and_b32_e32 v71, 0xffff0000, v203
	v_pk_add_f32 v[68:69], v[64:65], v[68:69]
	v_pk_add_f32 v[74:75], v[62:63], v[74:75]
	v_pk_add_f32 v[70:71], v[60:61], v[70:71]
	v_pk_add_f32 v[76:77], v[58:59], v[76:77]
	v_cvt_pk_bf16_f32 v58, v74, v75
	v_cvt_pk_bf16_f32 v59, v68, v69
	v_mul_f32_e32 v75, v75, v75
	v_cvt_pk_bf16_f32 v60, v76, v77
	v_cvt_pk_bf16_f32 v61, v70, v71
	s_nop 0
	v_mul_f32_e32 v69, v69, v69
	v_mul_f32_e32 v77, v77, v77
	v_fmac_f32_e32 v75, v74, v74
	v_fmac_f32_e32 v69, v68, v68
	v_mul_f32_e32 v71, v71, v71
	v_fmac_f32_e32 v77, v76, v76
	v_add_f32_e32 v68, v75, v69
	v_fmac_f32_e32 v71, v70, v70
	v_add_f32_e32 v68, v77, v68
	v_add_f32_e32 v74, v71, v68
	global_store_dwordx4 v[72:73], v[58:61], off
	s_waitcnt vmcnt(19)
	v_lshlrev_b32_e32 v68, 16, v204
	v_and_b32_e32 v69, 0xffff0000, v204
	v_lshlrev_b32_e32 v62, 16, v205
	v_and_b32_e32 v63, 0xffff0000, v205
	v_lshlrev_b32_e32 v70, 16, v206
	v_and_b32_e32 v71, 0xffff0000, v206
	v_lshlrev_b32_e32 v64, 16, v207
	v_and_b32_e32 v65, 0xffff0000, v207
	v_pk_add_f32 v[56:57], v[56:57], v[62:63]
	v_pk_add_f32 v[54:55], v[54:55], v[68:69]
	v_pk_add_f32 v[62:63], v[52:53], v[64:65]
	v_pk_add_f32 v[64:65], v[50:51], v[70:71]
	v_mul_f32_e32 v50, v55, v55
	v_mul_f32_e32 v51, v57, v57
	v_mul_f32_e32 v52, v65, v65
	v_fmac_f32_e32 v50, v54, v54
	v_fmac_f32_e32 v51, v56, v56
	v_mul_f32_e32 v53, v63, v63
	v_fmac_f32_e32 v52, v64, v64
	v_add_f32_e32 v50, v50, v51
	v_add_f32_e32 v50, v52, v50
	v_fmac_f32_e32 v53, v62, v62
	v_add_f32_e32 v50, v53, v50
	v_add_f32_e32 v50, v74, v50
	ds_bpermute_b32 v51, v122, v50
	v_cvt_pk_bf16_f32 v52, v54, v55
	v_cvt_pk_bf16_f32 v53, v56, v57
	v_cvt_pk_bf16_f32 v54, v64, v65
	v_cvt_pk_bf16_f32 v55, v62, v63
	s_waitcnt lgkmcnt(0)
	v_add_f32_e32 v50, v50, v51
	ds_bpermute_b32 v51, v116, v50
	global_store_dwordx4 v[72:73], v[52:55], off offset:256
	s_and_saveexec_b64 s[0:1], vcc
	s_cbranch_execz .LBB0_1233
	v_lshl_add_u64 v[52:53], v[66:67], 2, s[8:9]
	s_waitcnt lgkmcnt(0)
	v_add_f32_e32 v50, v50, v51
	global_atomic_add_f32 v[52:53], v50, off
.LBB0_1233:
	s_or_b64 exec, exec, s[0:1]
	v_add_u32_e32 v50, 0x90, v144
	s_waitcnt lgkmcnt(0)
	v_ashrrev_i32_e32 v51, 31, v50
	v_lshlrev_b64 v[52:53], 12, v[50:51]
	v_lshl_add_u64 v[52:53], s[62:63], 0, v[52:53]
	v_lshl_add_u64 v[56:57], v[142:143], 1, v[52:53]
	s_nop 0
	s_waitcnt vmcnt(20)
	v_lshlrev_b32_e32 v58, 16, v208
	v_and_b32_e32 v59, 0xffff0000, v208
	v_lshlrev_b32_e32 v52, 16, v209
	v_and_b32_e32 v53, 0xffff0000, v209
	v_lshlrev_b32_e32 v60, 16, v210
	v_and_b32_e32 v61, 0xffff0000, v210
	v_lshlrev_b32_e32 v54, 16, v211
	v_and_b32_e32 v55, 0xffff0000, v211
	v_pk_add_f32 v[52:53], v[48:49], v[52:53]
	v_pk_add_f32 v[58:59], v[46:47], v[58:59]
	v_pk_add_f32 v[54:55], v[44:45], v[54:55]
	v_pk_add_f32 v[60:61], v[42:43], v[60:61]
	v_cvt_pk_bf16_f32 v42, v58, v59
	v_cvt_pk_bf16_f32 v43, v52, v53
	v_mul_f32_e32 v59, v59, v59
	v_cvt_pk_bf16_f32 v44, v60, v61
	v_cvt_pk_bf16_f32 v45, v54, v55
	s_nop 0
	v_mul_f32_e32 v53, v53, v53
	v_mul_f32_e32 v61, v61, v61
	v_fmac_f32_e32 v59, v58, v58
	v_fmac_f32_e32 v53, v52, v52
	v_mul_f32_e32 v55, v55, v55
	v_fmac_f32_e32 v61, v60, v60
	v_add_f32_e32 v52, v59, v53
	v_fmac_f32_e32 v55, v54, v54
	v_add_f32_e32 v52, v61, v52
	v_add_f32_e32 v58, v55, v52
	global_store_dwordx4 v[56:57], v[42:45], off
	s_waitcnt vmcnt(20)
	v_lshlrev_b32_e32 v52, 16, v212
	v_and_b32_e32 v53, 0xffff0000, v212
	v_lshlrev_b32_e32 v46, 16, v213
	v_and_b32_e32 v47, 0xffff0000, v213
	v_lshlrev_b32_e32 v54, 16, v214
	v_and_b32_e32 v55, 0xffff0000, v214
	v_lshlrev_b32_e32 v48, 16, v215
	v_and_b32_e32 v49, 0xffff0000, v215
	v_pk_add_f32 v[40:41], v[40:41], v[46:47]
	v_pk_add_f32 v[38:39], v[38:39], v[52:53]
	v_pk_add_f32 v[46:47], v[36:37], v[48:49]
	v_pk_add_f32 v[48:49], v[34:35], v[54:55]
	v_mul_f32_e32 v34, v39, v39
	v_mul_f32_e32 v35, v41, v41
	v_mul_f32_e32 v36, v49, v49
	v_fmac_f32_e32 v34, v38, v38
	v_fmac_f32_e32 v35, v40, v40
	v_mul_f32_e32 v37, v47, v47
	v_fmac_f32_e32 v36, v48, v48
	v_add_f32_e32 v34, v34, v35
	v_add_f32_e32 v34, v36, v34
	v_fmac_f32_e32 v37, v46, v46
	v_add_f32_e32 v34, v37, v34
	v_add_f32_e32 v34, v58, v34
	ds_bpermute_b32 v35, v122, v34
	v_cvt_pk_bf16_f32 v36, v38, v39
	v_cvt_pk_bf16_f32 v37, v40, v41
	v_cvt_pk_bf16_f32 v38, v48, v49
	v_cvt_pk_bf16_f32 v39, v46, v47
	s_waitcnt lgkmcnt(0)
	v_add_f32_e32 v34, v34, v35
	ds_bpermute_b32 v35, v116, v34
	global_store_dwordx4 v[56:57], v[36:39], off offset:256
	s_and_saveexec_b64 s[0:1], vcc
	s_cbranch_execz .LBB0_1235
	v_lshl_add_u64 v[36:37], v[50:51], 2, s[8:9]
	s_waitcnt lgkmcnt(0)
	v_add_f32_e32 v34, v34, v35
	global_atomic_add_f32 v[36:37], v34, off
.LBB0_1235:
	s_or_b64 exec, exec, s[0:1]
	v_add_u32_e32 v34, 0xa0, v144
	s_waitcnt lgkmcnt(0)
	v_ashrrev_i32_e32 v35, 31, v34
	v_lshlrev_b64 v[36:37], 12, v[34:35]
	v_lshl_add_u64 v[36:37], s[62:63], 0, v[36:37]
	v_lshl_add_u64 v[40:41], v[142:143], 1, v[36:37]
	s_nop 0
	s_waitcnt vmcnt(21)
	v_lshlrev_b32_e32 v42, 16, v216
	v_and_b32_e32 v43, 0xffff0000, v216
	v_lshlrev_b32_e32 v36, 16, v217
	v_and_b32_e32 v37, 0xffff0000, v217
	v_lshlrev_b32_e32 v44, 16, v218
	v_and_b32_e32 v45, 0xffff0000, v218
	v_lshlrev_b32_e32 v38, 16, v219
	v_and_b32_e32 v39, 0xffff0000, v219
	v_pk_add_f32 v[36:37], v[32:33], v[36:37]
	v_pk_add_f32 v[42:43], v[30:31], v[42:43]
	v_pk_add_f32 v[38:39], v[28:29], v[38:39]
	v_pk_add_f32 v[44:45], v[26:27], v[44:45]
	v_cvt_pk_bf16_f32 v26, v42, v43
	v_cvt_pk_bf16_f32 v27, v36, v37
	v_mul_f32_e32 v43, v43, v43
	v_cvt_pk_bf16_f32 v28, v44, v45
	v_cvt_pk_bf16_f32 v29, v38, v39
	s_nop 0
	v_mul_f32_e32 v37, v37, v37
	v_mul_f32_e32 v45, v45, v45
	v_fmac_f32_e32 v43, v42, v42
	v_fmac_f32_e32 v37, v36, v36
	v_mul_f32_e32 v39, v39, v39
	v_fmac_f32_e32 v45, v44, v44
	v_add_f32_e32 v36, v43, v37
	v_fmac_f32_e32 v39, v38, v38
	v_add_f32_e32 v36, v45, v36
	v_add_f32_e32 v42, v39, v36
	global_store_dwordx4 v[40:41], v[26:29], off
	s_waitcnt vmcnt(21)
	v_lshlrev_b32_e32 v36, 16, v220
	v_and_b32_e32 v37, 0xffff0000, v220
	v_lshlrev_b32_e32 v30, 16, v221
	v_and_b32_e32 v31, 0xffff0000, v221
	v_lshlrev_b32_e32 v38, 16, v222
	v_and_b32_e32 v39, 0xffff0000, v222
	v_lshlrev_b32_e32 v32, 16, v223
	v_and_b32_e32 v33, 0xffff0000, v223
	v_pk_add_f32 v[24:25], v[24:25], v[30:31]
	v_pk_add_f32 v[22:23], v[22:23], v[36:37]
	v_pk_add_f32 v[30:31], v[20:21], v[32:33]
	v_pk_add_f32 v[32:33], v[18:19], v[38:39]
	v_mul_f32_e32 v18, v23, v23
	v_mul_f32_e32 v19, v25, v25
	v_mul_f32_e32 v20, v33, v33
	v_fmac_f32_e32 v18, v22, v22
	v_fmac_f32_e32 v19, v24, v24
	v_mul_f32_e32 v21, v31, v31
	v_fmac_f32_e32 v20, v32, v32
	v_add_f32_e32 v18, v18, v19
	v_add_f32_e32 v18, v20, v18
	v_fmac_f32_e32 v21, v30, v30
	v_add_f32_e32 v18, v21, v18
	v_add_f32_e32 v18, v42, v18
	ds_bpermute_b32 v19, v122, v18
	v_cvt_pk_bf16_f32 v20, v22, v23
	v_cvt_pk_bf16_f32 v21, v24, v25
	v_cvt_pk_bf16_f32 v22, v32, v33
	v_cvt_pk_bf16_f32 v23, v30, v31
	s_waitcnt lgkmcnt(0)
	v_add_f32_e32 v18, v18, v19
	ds_bpermute_b32 v19, v116, v18
	global_store_dwordx4 v[40:41], v[20:23], off offset:256
	s_and_saveexec_b64 s[0:1], vcc
	s_cbranch_execz .LBB0_1237
	v_lshl_add_u64 v[20:21], v[34:35], 2, s[8:9]
	s_waitcnt lgkmcnt(0)
	v_add_f32_e32 v18, v18, v19
	global_atomic_add_f32 v[20:21], v18, off
.LBB0_1237:
	s_or_b64 exec, exec, s[0:1]
	v_add_u32_e32 v18, 0xb0, v144
	s_waitcnt lgkmcnt(0)
	v_ashrrev_i32_e32 v19, 31, v18
	v_lshlrev_b64 v[20:21], 12, v[18:19]
	v_lshl_add_u64 v[20:21], s[62:63], 0, v[20:21]
	v_lshl_add_u64 v[24:25], v[142:143], 1, v[20:21]
	s_nop 0
	s_waitcnt vmcnt(22)
	v_lshlrev_b32_e32 v26, 16, v224
	v_and_b32_e32 v27, 0xffff0000, v224
	v_lshlrev_b32_e32 v20, 16, v225
	v_and_b32_e32 v21, 0xffff0000, v225
	v_lshlrev_b32_e32 v28, 16, v226
	v_and_b32_e32 v29, 0xffff0000, v226
	v_lshlrev_b32_e32 v22, 16, v227
	v_and_b32_e32 v23, 0xffff0000, v227
	v_pk_add_f32 v[20:21], v[16:17], v[20:21]
	v_pk_add_f32 v[26:27], v[14:15], v[26:27]
	v_pk_add_f32 v[22:23], v[12:13], v[22:23]
	v_pk_add_f32 v[28:29], v[10:11], v[28:29]
	v_cvt_pk_bf16_f32 v10, v26, v27
	v_cvt_pk_bf16_f32 v11, v20, v21
	v_mul_f32_e32 v27, v27, v27
	v_cvt_pk_bf16_f32 v12, v28, v29
	v_cvt_pk_bf16_f32 v13, v22, v23
	s_nop 0
	v_mul_f32_e32 v21, v21, v21
	v_mul_f32_e32 v29, v29, v29
	v_fmac_f32_e32 v27, v26, v26
	v_fmac_f32_e32 v21, v20, v20
	v_mul_f32_e32 v23, v23, v23
	v_fmac_f32_e32 v29, v28, v28
	v_add_f32_e32 v20, v27, v21
	v_fmac_f32_e32 v23, v22, v22
	v_add_f32_e32 v20, v29, v20
	v_add_f32_e32 v26, v23, v20
	global_store_dwordx4 v[24:25], v[10:13], off
	s_waitcnt vmcnt(22)
	v_lshlrev_b32_e32 v20, 16, v232
	v_and_b32_e32 v21, 0xffff0000, v232
	v_lshlrev_b32_e32 v14, 16, v233
	v_and_b32_e32 v15, 0xffff0000, v233
	v_lshlrev_b32_e32 v22, 16, v234
	v_and_b32_e32 v23, 0xffff0000, v234
	v_lshlrev_b32_e32 v16, 16, v235
	v_and_b32_e32 v17, 0xffff0000, v235
	v_pk_add_f32 v[8:9], v[8:9], v[14:15]
	v_pk_add_f32 v[6:7], v[6:7], v[20:21]
	v_pk_add_f32 v[14:15], v[4:5], v[16:17]
	v_pk_add_f32 v[16:17], v[2:3], v[22:23]
	v_mul_f32_e32 v2, v7, v7
	v_mul_f32_e32 v3, v9, v9
	v_mul_f32_e32 v4, v17, v17
	v_fmac_f32_e32 v2, v6, v6
	v_fmac_f32_e32 v3, v8, v8
	v_mul_f32_e32 v5, v15, v15
	v_fmac_f32_e32 v4, v16, v16
	v_add_f32_e32 v2, v2, v3
	v_add_f32_e32 v2, v4, v2
	v_fmac_f32_e32 v5, v14, v14
	v_add_f32_e32 v2, v5, v2
	v_add_f32_e32 v2, v26, v2
	ds_bpermute_b32 v3, v122, v2
	v_cvt_pk_bf16_f32 v4, v6, v7
	v_cvt_pk_bf16_f32 v5, v8, v9
	v_cvt_pk_bf16_f32 v6, v16, v17
	v_cvt_pk_bf16_f32 v7, v14, v15
	s_waitcnt lgkmcnt(0)
	v_add_f32_e32 v2, v2, v3
	ds_bpermute_b32 v3, v116, v2
	global_store_dwordx4 v[24:25], v[4:7], off offset:256
	s_and_saveexec_b64 s[0:1], vcc
	s_cbranch_execz .LBB0_1239
	v_lshl_add_u64 v[4:5], v[18:19], 2, s[8:9]
	s_waitcnt lgkmcnt(0)
	v_add_f32_e32 v2, v2, v3
	global_atomic_add_f32 v[4:5], v2, off

	.amdhsa_kernel _Z10fwd_kernel4Args
		.amdhsa_group_segment_fixed_size 0
		.amdhsa_private_segment_fixed_size 0
		.amdhsa_kernarg_size 432
		.amdhsa_user_sgpr_count 2
		.amdhsa_user_sgpr_dispatch_ptr 0
		.amdhsa_user_sgpr_queue_ptr 0
		.amdhsa_user_sgpr_kernarg_segment_ptr 1
		.amdhsa_user_sgpr_dispatch_id 0
		.amdhsa_user_sgpr_kernarg_preload_length 0
		.amdhsa_user_sgpr_kernarg_preload_offset 0
		.amdhsa_user_sgpr_private_segment_size 0
		.amdhsa_uses_dynamic_stack 0
		.amdhsa_enable_private_segment 0
		.amdhsa_system_sgpr_workgroup_id_x 1
		.amdhsa_system_sgpr_workgroup_id_y 0
		.amdhsa_system_sgpr_workgroup_id_z 0
		.amdhsa_system_sgpr_workgroup_info 0
		.amdhsa_system_vgpr_workitem_id 2
		.amdhsa_next_free_vgpr 256
		.amdhsa_next_free_sgpr 100
		.amdhsa_accum_offset 256
		.amdhsa_reserve_vcc 1
		.amdhsa_float_round_mode_32 0
		.amdhsa_float_round_mode_16_64 0
		.amdhsa_float_denorm_mode_32 3
		.amdhsa_float_denorm_mode_16_64 3
		.amdhsa_dx10_clamp 1
		.amdhsa_ieee_mode 1
		.amdhsa_fp16_overflow 0
		.amdhsa_tg_split 0
		.amdhsa_exception_fp_ieee_invalid_op 0
		.amdhsa_exception_fp_denorm_src 0
		.amdhsa_exception_fp_ieee_div_zero 0
		.amdhsa_exception_fp_ieee_overflow 0
		.amdhsa_exception_fp_ieee_underflow 0
		.amdhsa_exception_fp_ieee_inexact 0
		.amdhsa_exception_int_div_zero 0
	.end_amdhsa_kernel
